# FoX unit prologue: all F2 gather loads issued together with the Q loads (one memory round trip for the whole prologue)
# baseline (speedup 1.0000x reference)
; __device__ __forceinline__ void fox_unit(int b, int hh, int qb, const bf16_t* Q, const bf16_t* __restrict__ K, const bf16_t* __restrict__ V, bf16_t* O, ...
;     ...
;     for (int d0 = 0; d0 < 4; ++d0) { qr[d0] = *reinterpret_cast<const bf16x8*>(Qw + (long)r32 * DM + d0 * 16 + hi * 8);
; #pragma unroll
;         for (int j = 0; j < 8; ++j) { const float f = __builtin_bit_cast(float, (unsigned)(unsigned short)qr[d0][j] << 16); qn2 += f * f; } }
;     qn2 += other_half(qn2);
;     const float kn = sqrtf(2.0f * __uint_as_float(KMAX[b * 8 + hh])) * 1.01f;
;     const float zq = sqrtf(qn2) * kn * 1.01f + 1.0f;
;     const float ft2 = Frow[qw0 + r32];
;     const float f2q0 = Frow[q0];
;     int jp_last0;
;     { bool c = false; if (lane >= 1 && lane < NT / 2) c = (f2q0 - Frow[128 * lane - 1]) < -128.0f;
;       const unsigned long long mk = __ballot(c); jp_last0 = mk ? 63 - __builtin_clzll(mk) : 0; }
;     int jp_lastw;
;     { const float f2w0 = Frow[qw0]; bool c = false; if (lane >= 1 && lane < NT / 2) c = (f2w0 - Frow[128 * lane - 1]) < -128.0f;
;       const unsigned long long mk = __ballot(c); jp_lastw = mk ? 63 - __builtin_clzll(mk) : 0; }
.LBB0_413:
	s_lshl_b32 s7, s15, 5
	v_writelane_b32 v249, s16, 60
	s_add_i32 s70, s7, s10
	v_writelane_b32 v249, s15, 61
	s_add_i32 s80, s70, s12
	s_lshl_b32 s6, s16, 6
	s_lshl_b64 s[12:13], s[80:81], 11
	v_readlane_b32 s14, v249, 23
	v_readlane_b32 s15, v249, 24
	s_add_u32 s12, s14, s12
	s_addc_u32 s13, s15, s13
	s_lshl_b32 s6, s6, 1
	s_add_u32 s12, s12, s6
	s_addc_u32 s13, s13, 0
	v_lshlrev_b32_e32 v2, 1, v134
	v_lshl_add_u64 v[4:5], s[12:13], 0, v[2:3]
	v_lshlrev_b32_e32 v2, 1, v136
	v_lshl_add_u64 v[4:5], v[4:5], 0, v[2:3]
	global_load_dwordx4 v[118:121], v[4:5], off
	global_load_dwordx4 v[122:125], v[4:5], off offset:32
	global_load_dwordx4 v[126:129], v[4:5], off offset:64
	global_load_dwordx4 v[130:133], v[4:5], off offset:96
	v_writelane_b32 v249, s6, 62
	s_lshl_b32 s6, s11, 2
	v_readlane_b32 s12, v249, 21
	v_readlane_b32 s13, v249, 22
	s_add_u32 s12, s12, s6
	s_addc_u32 s13, s13, 0
	s_lshl_b32 s6, s2, 2
	s_lshl_b32 s2, s5, 2
	v_readlane_b32 s14, v249, 43
	v_or_b32_e32 v2, s70, v182
	v_mov_b32_e32 v6, s2
	v_readlane_b32 s15, v249, 44
	v_lshl_add_u64 v[4:5], v[2:3], 2, s[12:13]
	s_nop 3
	global_load_dword v6, v6, s[14:15] offset:256
	s_nop 0
	global_load_dword v2, v[4:5], off
	s_add_i32 s5, s6, 4
	s_lshr_b32 s2, s5, 1
	v_readlane_b32 s14, v249, 47
	v_cmp_gt_u32_e32 vcc, s2, v180
	v_readlane_b32 s15, v249, 48
	s_mov_b64 s[16:17], 0
	v_lshl_add_u64 v[4:5], v[150:151], 2, s[12:13]
	s_and_b64 s[14:15], s[14:15], vcc
	s_mov_b64 s[20:21], 0
	s_mov_b64 s[98:99], exec
	s_and_b64 exec, exec, s[14:15]
	s_cbranch_execz .Lfox_pro_nold
	s_mov_b32 s100, s10
	s_mov_b32 s101, s81
	s_lshl_b64 s[100:101], s[100:101], 2
	s_add_u32 s100, s12, s100
	s_addc_u32 s101, s13, s101
	global_load_dword v245, v3, s[100:101]
	global_load_dword v246, v[4:5], off offset:-4
	s_mov_b32 s100, s70
	s_mov_b32 s101, s81
	s_lshl_b64 s[100:101], s[100:101], 2
	s_add_u32 s100, s12, s100
	s_addc_u32 s101, s13, s101
	global_load_dword v244, v3, s[100:101]
.Lfox_pro_nold:
	s_mov_b64 exec, s[98:99]
	s_waitcnt vmcnt(5)
	v_and_b32_e32 v18, 0xffff0000, v118
	v_lshlrev_b32_e32 v7, 16, v118
	v_mul_f32_e32 v37, v18, v18
	v_lshlrev_b32_e32 v19, 16, v119
	v_fmac_f32_e32 v37, v7, v7
	v_and_b32_e32 v20, 0xffff0000, v119
	v_fmac_f32_e32 v37, v19, v19
	v_lshlrev_b32_e32 v21, 16, v120
	v_fmac_f32_e32 v37, v20, v20
	v_and_b32_e32 v22, 0xffff0000, v120
	v_fmac_f32_e32 v37, v21, v21
	v_lshlrev_b32_e32 v23, 16, v121
	v_fmac_f32_e32 v37, v22, v22
	v_and_b32_e32 v24, 0xffff0000, v121
	v_fmac_f32_e32 v37, v23, v23
	s_waitcnt vmcnt(4)
	v_lshlrev_b32_e32 v25, 16, v122
	v_fmac_f32_e32 v37, v24, v24
	v_and_b32_e32 v26, 0xffff0000, v122
	v_fmac_f32_e32 v37, v25, v25
	v_lshlrev_b32_e32 v27, 16, v123
	v_fmac_f32_e32 v37, v26, v26
	v_and_b32_e32 v28, 0xffff0000, v123
	v_fmac_f32_e32 v37, v27, v27
	v_lshlrev_b32_e32 v29, 16, v124
	v_fmac_f32_e32 v37, v28, v28
	v_and_b32_e32 v30, 0xffff0000, v124
	v_fmac_f32_e32 v37, v29, v29
	v_lshlrev_b32_e32 v31, 16, v125
	v_fmac_f32_e32 v37, v30, v30
	v_and_b32_e32 v32, 0xffff0000, v125
	v_fmac_f32_e32 v37, v31, v31
	s_waitcnt vmcnt(3)
	v_lshlrev_b32_e32 v33, 16, v126
	v_fmac_f32_e32 v37, v32, v32
	v_and_b32_e32 v34, 0xffff0000, v126
	v_fmac_f32_e32 v37, v33, v33
	v_lshlrev_b32_e32 v35, 16, v127
	v_fmac_f32_e32 v37, v34, v34
	v_and_b32_e32 v36, 0xffff0000, v127
	v_and_b32_e32 v9, 0xffff0000, v128
	v_lshlrev_b32_e32 v8, 16, v128
	v_fmac_f32_e32 v37, v35, v35
	v_pk_mul_f32 v[8:9], v[8:9], v[8:9]
	v_fmac_f32_e32 v37, v36, v36
	v_and_b32_e32 v11, 0xffff0000, v129
	v_lshlrev_b32_e32 v10, 16, v129
	v_add_f32_e32 v7, v8, v37
	v_pk_mul_f32 v[10:11], v[10:11], v[10:11]
	v_add_f32_e32 v7, v9, v7
	s_waitcnt vmcnt(2)
	v_and_b32_e32 v13, 0xffff0000, v130
	v_lshlrev_b32_e32 v12, 16, v130
	v_add_f32_e32 v7, v10, v7
	v_pk_mul_f32 v[12:13], v[12:13], v[12:13]
	v_add_f32_e32 v7, v11, v7
	v_and_b32_e32 v15, 0xffff0000, v131
	v_lshlrev_b32_e32 v14, 16, v131
	v_add_f32_e32 v7, v12, v7
	v_pk_mul_f32 v[14:15], v[14:15], v[14:15]
	v_add_f32_e32 v7, v13, v7
	v_and_b32_e32 v17, 0xffff0000, v132
	v_lshlrev_b32_e32 v16, 16, v132
	v_add_f32_e32 v7, v14, v7
	v_pk_mul_f32 v[16:17], v[16:17], v[16:17]
	v_add_f32_e32 v7, v15, v7
	v_and_b32_e32 v19, 0xffff0000, v133
	v_lshlrev_b32_e32 v18, 16, v133
	v_add_f32_e32 v7, v16, v7
	v_pk_mul_f32 v[18:19], v[18:19], v[18:19]
	v_add_f32_e32 v7, v17, v7
	v_add_f32_e32 v7, v18, v7
	v_add_f32_e32 v7, v19, v7
	v_mov_b32_e32 v8, v7
	v_mov_b32_e32 v9, v7
	s_nop 1
	v_permlane32_swap_b32_e32 v8, v9
	s_and_saveexec_b64 s[18:19], s[14:15]
	s_cbranch_execz .LBB0_415
	s_mov_b32 s5, 0xc3000000
	s_waitcnt vmcnt(0)
	v_sub_f32_e32 v10, v245, v246
	v_cmp_gt_f32_e32 vcc, s5, v10
	s_and_b64 s[20:21], vcc, exec
.LBB0_415:
	s_or_b64 exec, exec, s[18:19]
	v_cndmask_b32_e64 v10, 0, 1, s[20:21]
	v_cmp_ne_u32_e32 vcc, 0, v10
	s_and_saveexec_b64 s[10:11], s[14:15]
	s_cbranch_execz .LBB0_417
	s_mov_b32 s71, s81
	s_lshl_b64 s[14:15], s[70:71], 2
	s_add_u32 s12, s12, s14
	s_addc_u32 s13, s13, s15
	s_mov_b32 s5, 0xc3000000
	v_sub_f32_e32 v4, v244, v246
	v_cmp_gt_f32_e64 s[12:13], s5, v4
	s_and_b64 s[16:17], s[12:13], exec
